# elem phase attention-merge loop: og row loads issued together with the lse loads (one round trip per iteration instead of two)
# speedup vs baseline: 1.0026x; 1.0026x over previous
.LBB0_503:
	v_alignbit_b32 v10, v1, v0, 5
	v_mad_u64_u32 v[6:7], s[4:5], v10, 48, s[8:9]
	v_mov_b32_e32 v8, v7
	v_lshrrev_b32_e32 v11, 5, v1
	v_bfe_u32 v5, v0, 3, 2
	v_mad_u64_u32 v[8:9], s[4:5], v11, 48, v[8:9]
	v_mov_b32_e32 v7, v8
	v_lshlrev_b32_e32 v136, 2, v5
	v_lshl_add_u64 v[6:7], v[6:7], 0, v[136:137]
	global_load_dword v32, v[6:7], off
	global_load_dword v33, v[6:7], off offset:16
	s_nop 0
	global_load_dword v34, v[6:7], off offset:32
	v_lshlrev_b32_e32 v136, 7, v5
	v_lshlrev_b32_e32 v5, 1, v2
	v_and_b32_e32 v26, 0x70, v5
	v_mov_b32_e32 v27, v137
	v_lshrrev_b64 v[18:19], 5, v[0:1]
	v_lshl_add_u64 v[0:1], v[0:1], 0, s[10:11]
	v_lshl_add_u64 v[2:3], v[2:3], 0, s[26:27]
	v_mov_b64_e32 v[6:7], s[6:7]
	v_mad_u64_u32 v[6:7], s[4:5], v10, s14, v[6:7]
	v_mov_b32_e32 v8, v7
	v_mad_u64_u32 v[8:9], s[4:5], v11, s14, v[8:9]
	v_mov_b32_e32 v7, v8
	v_lshl_add_u64 v[6:7], v[6:7], 0, v[136:137]
	v_lshl_add_u64 v[14:15], v[6:7], 0, v[26:27]
	global_load_dwordx4 v[6:9], v[14:15], off
	global_load_dwordx4 v[10:13], v[14:15], off offset:512
	s_nop 0
	global_load_dwordx4 v[14:17], v[14:15], off offset:1024
	s_waitcnt vmcnt(3)
	v_max3_f32 v35, v32, v33, v34
	v_sub_f32_e32 v32, v32, v35
	v_sub_f32_e32 v33, v33, v35
	v_mul_f32_e32 v32, 0x3fb8aa3b, v32
	v_mul_f32_e32 v33, 0x3fb8aa3b, v33
	v_sub_f32_e32 v34, v34, v35
	v_exp_f32_e32 v32, v32
	v_exp_f32_e32 v33, v33
	v_mul_f32_e32 v34, 0x3fb8aa3b, v34
	v_exp_f32_e32 v34, v34
	v_add_f32_e32 v35, v32, v33
	v_add_f32_e32 v35, v34, v35
	v_rcp_f32_e32 v35, v35
	s_nop 0
	v_mul_f32_e32 v20, v32, v35
	v_mul_f32_e32 v22, v33, v35
	v_mul_f32_e32 v24, v34, v35
	s_mov_b64 s[4:5], 0x7ffff
	v_cmp_lt_u64_e32 vcc, s[4:5], v[0:1]
	s_or_b64 s[0:1], vcc, s[0:1]
	s_waitcnt vmcnt(2)
	v_lshlrev_b32_e32 v28, 16, v6
	v_and_b32_e32 v29, 0xffff0000, v6
	v_lshlrev_b32_e32 v6, 16, v7
	v_and_b32_e32 v7, 0xffff0000, v7
	s_waitcnt vmcnt(1)
	v_lshlrev_b32_e32 v30, 16, v10
	v_and_b32_e32 v31, 0xffff0000, v10
	v_pk_fma_f32 v[6:7], v[20:21], v[6:7], 0 op_sel_hi:[0,1,0]
	v_lshlrev_b32_e32 v10, 16, v11
	v_and_b32_e32 v11, 0xffff0000, v11
	v_pk_fma_f32 v[6:7], v[22:23], v[10:11], v[6:7] op_sel_hi:[0,1,1]
	s_waitcnt vmcnt(0)
	v_lshlrev_b32_e32 v10, 16, v15
	v_and_b32_e32 v11, 0xffff0000, v15
	v_pk_fma_f32 v[28:29], v[20:21], v[28:29], 0 op_sel_hi:[0,1,0]
	v_pk_fma_f32 v[10:11], v[24:25], v[10:11], v[6:7] op_sel_hi:[0,1,1]
	v_lshlrev_b32_e32 v6, 16, v8
	v_and_b32_e32 v7, 0xffff0000, v8
	v_pk_fma_f32 v[28:29], v[22:23], v[30:31], v[28:29] op_sel_hi:[0,1,1]
	v_lshlrev_b32_e32 v30, 16, v14
	v_and_b32_e32 v31, 0xffff0000, v14
	v_pk_fma_f32 v[6:7], v[20:21], v[6:7], 0 op_sel_hi:[0,1,0]
	v_lshlrev_b32_e32 v14, 16, v12
	v_and_b32_e32 v15, 0xffff0000, v12
	v_pk_fma_f32 v[6:7], v[22:23], v[14:15], v[6:7] op_sel_hi:[0,1,1]
	v_lshlrev_b32_e32 v14, 16, v16
	v_and_b32_e32 v15, 0xffff0000, v16
	v_pk_fma_f32 v[14:15], v[24:25], v[14:15], v[6:7] op_sel_hi:[0,1,1]
	v_lshlrev_b32_e32 v6, 16, v9
	v_and_b32_e32 v7, 0xffff0000, v9
	v_pk_fma_f32 v[6:7], v[20:21], v[6:7], 0 op_sel_hi:[0,1,0]
	v_lshlrev_b32_e32 v8, 16, v13
	v_and_b32_e32 v9, 0xffff0000, v13
	v_pk_fma_f32 v[6:7], v[22:23], v[8:9], v[6:7] op_sel_hi:[0,1,1]
	v_lshlrev_b32_e32 v8, 16, v17
	v_and_b32_e32 v9, 0xffff0000, v17
	v_pk_fma_f32 v[12:13], v[24:25], v[8:9], v[6:7] op_sel_hi:[0,1,1]
	v_cvt_pk_bf16_f32 v7, v10, v11
	v_lshlrev_b64 v[10:11], 9, v[18:19]
	v_lshl_add_u64 v[10:11], s[12:13], 0, v[10:11]
	v_pk_fma_f32 v[28:29], v[24:25], v[30:31], v[28:29] op_sel_hi:[0,1,1]
	v_lshl_add_u64 v[10:11], v[10:11], 0, v[136:137]
	v_cvt_pk_bf16_f32 v6, v28, v29
	v_cvt_pk_bf16_f32 v8, v14, v15
	v_cvt_pk_bf16_f32 v9, v12, v13
	v_lshl_add_u64 v[10:11], v[10:11], 0, v[26:27]
	global_store_dwordx4 v[10:11], v[6:9], off
	s_andn2_b64 exec, exec, s[0:1]
	s_cbranch_execnz .LBB0_503
	s_or_b64 exec, exec, s[0:1]
